# final RMSNorm output stores without the non-temporal hint
# baseline (speedup 1.0000x reference)
; template <class T> __device__ __forceinline__ void gst_nt(void* p, T v) { __builtin_nontemporal_store(v, (GAS T*)p); }
; template <class T> __device__ __forceinline__ T gld_nt(const void* p) { return __builtin_nontemporal_load((const GAS T*)p); }
; __device__ __forceinline__ float rstd_of(float ss, float inv_n) { return __builtin_amdgcn_rsqf(ss * inv_n + RMS_EPS); }
; __device__ __forceinline__ float bf_lo(unsigned w) { return __uint_as_float(w << 16); }
; __device__ __forceinline__ float bf_hi(unsigned w) { return __uint_as_float(w & 0xffff0000u); }
; __global__ void __launch_bounds__(NWAVES * 64, 2) mk_fwd(Args args) {
;     ...
;             const float* gF = ka->in[18];
;             const f32x4* gr = (const f32x4*)gF + lane;
;             for (int m0 = gw; m0 < M; m0 += 4 * NGW) {
;                 int mr[4]; float ss[4]; u32x2 r[4][8];
; #pragma unroll
;                 for (int q = 0; q < 4; ++q) { mr[q] = (m0 + q * NGW < M) ? m0 + q * NGW : m0; ss[q] = gld<float>(ssh3 + mr[q]); }
; #pragma unroll
;                 for (int q = 0; q < 4; ++q)
; #pragma unroll
;                     for (int j = 0; j < 8; ++j) r[q][j] = gld_nt<u32x2>((const u32x2*)(HB + (size_t)mr[q] * D) + lane + 64 * j);
; #pragma unroll
;                 for (int j = 0; j < 8; ++j) { const f32x4 g = gld<f32x4>(gr + 64 * j);
; #pragma unroll
;                     for (int q = 0; q < 4; ++q) if (q == 0 || mr[q] != m0) {
;                         const float rs = pg8::rstd_of(ss[q], 1.0f / 2048.0f);
;                         gst_nt<f32x4>((f32x4*)(ka->out + (size_t)mr[q] * D) + lane + 64 * j, (f32x4){bf_lo(r[q][j].x), bf_hi(r[q][j].x), bf_lo(r[q][j].y), bf_hi(r[q][j].y)} * g * rs); }
;                 }
;             }
.LBB0_303:
	s_add_u32 s2, s16, s9
	s_addc_u32 s3, s17, s10
	global_load_dword v36, v193, s[2:3]
	s_add_i32 s2, s82, s7
	s_cmpk_lt_i32 s2, 0x4000
	s_cselect_b32 s50, s2, s7
	s_ashr_i32 s51, s50, 31
	s_lshl_b64 s[2:3], s[50:51], 2
	s_add_u32 s2, s83, s2
	s_addc_u32 s3, s84, s3
	global_load_dword v84, v193, s[2:3]
	s_add_i32 s2, s8, s7
	s_cmpk_lt_i32 s2, 0x4000
	s_cselect_b32 s44, s2, s7
	s_ashr_i32 s45, s44, 31
	s_lshl_b64 s[2:3], s[44:45], 2
	s_add_u32 s2, s83, s2
	s_addc_u32 s3, s84, s3
	global_load_dword v85, v193, s[2:3]
	s_mul_i32 s2, s79, 24
	s_add_i32 s2, s2, s7
	s_cmpk_lt_i32 s2, 0x4000
	s_cselect_b32 s2, s2, s7
	s_ashr_i32 s3, s2, 31
	s_lshl_b64 s[14:15], s[2:3], 2
	s_add_u32 s14, s83, s14
	s_addc_u32 s15, s84, s15
	v_lshl_add_u64 v[0:1], s[16:17], 0, v[18:19]
	s_mov_b32 s11, 0xa800000
	global_load_dword v37, v193, s[14:15]
	v_add_co_u32_e32 v86, vcc, s11, v0
	s_lshl_b64 s[14:15], s[50:51], 12
	s_nop 0
	v_addc_co_u32_e32 v87, vcc, 0, v1, vcc
	v_lshl_add_u64 v[0:1], v[4:5], 0, s[14:15]
	s_lshl_b64 s[14:15], s[44:45], 12
	global_load_dwordx2 v[76:77], v[86:87], off offset:512 nt
	global_load_dwordx2 v[68:69], v[86:87], off offset:1024 nt
	global_load_dwordx2 v[60:61], v[86:87], off offset:1536 nt
	global_load_dwordx2 v[52:53], v[86:87], off offset:2048 nt
	global_load_dwordx2 v[44:45], v[86:87], off offset:2560 nt
	global_load_dwordx2 v[34:35], v[86:87], off offset:3072 nt
	global_load_dwordx2 v[26:27], v[86:87], off offset:3584 nt
	global_load_dwordx2 v[82:83], v[0:1], off nt
	global_load_dwordx2 v[74:75], v[0:1], off offset:512 nt
	global_load_dwordx2 v[66:67], v[0:1], off offset:1024 nt
	global_load_dwordx2 v[58:59], v[0:1], off offset:1536 nt
	global_load_dwordx2 v[50:51], v[0:1], off offset:2048 nt
	global_load_dwordx2 v[42:43], v[0:1], off offset:2560 nt
	global_load_dwordx2 v[32:33], v[0:1], off offset:3072 nt
	global_load_dwordx2 v[24:25], v[0:1], off offset:3584 nt
	v_lshl_add_u64 v[0:1], v[4:5], 0, s[14:15]
	global_load_dwordx2 v[80:81], v[0:1], off nt
	global_load_dwordx2 v[72:73], v[0:1], off offset:512 nt
	global_load_dwordx2 v[64:65], v[0:1], off offset:1024 nt
	global_load_dwordx2 v[56:57], v[0:1], off offset:1536 nt
	global_load_dwordx2 v[48:49], v[0:1], off offset:2048 nt
	global_load_dwordx2 v[40:41], v[0:1], off offset:2560 nt
	global_load_dwordx2 v[30:31], v[0:1], off offset:3072 nt
	global_load_dwordx2 v[22:23], v[0:1], off offset:3584 nt
	s_lshl_b64 s[14:15], s[2:3], 12
	v_lshl_add_u64 v[0:1], v[4:5], 0, s[14:15]
	global_load_dwordx2 v[78:79], v[0:1], off nt
	global_load_dwordx2 v[70:71], v[0:1], off offset:512 nt
	global_load_dwordx2 v[62:63], v[0:1], off offset:1024 nt
	global_load_dwordx2 v[54:55], v[0:1], off offset:1536 nt
	global_load_dwordx2 v[46:47], v[0:1], off offset:2048 nt
	global_load_dwordx2 v[38:39], v[0:1], off offset:2560 nt
	global_load_dwordx2 v[28:29], v[0:1], off offset:3072 nt
	global_load_dwordx2 v[20:21], v[0:1], off offset:3584 nt
	s_nop 0
	global_load_dwordx4 v[0:3], v[6:7], off
	s_nop 0
	global_load_dwordx2 v[86:87], v[86:87], off nt
	s_cmp_lg_u32 s7, s50
	s_cselect_b64 s[14:15], -1, 0
	s_cmp_eq_u32 s7, s50
	v_lshlrev_b32_e32 v192, 4, v210
	s_waitcnt vmcnt(36)
	v_fmamk_f32 v36, v36, 0x3a000000, v246
	v_rsq_f32_e32 v36, v36
	s_waitcnt vmcnt(35)
	v_fmamk_f32 v84, v84, 0x3a000000, v246
	s_waitcnt vmcnt(0)
	v_lshlrev_b32_e32 v88, 16, v86
	v_and_b32_e32 v89, 0xffff0000, v86
	v_lshlrev_b32_e32 v86, 16, v87
	v_and_b32_e32 v87, 0xffff0000, v87
	v_pk_mul_f32 v[90:91], v[0:1], v[88:89]
	v_pk_mul_f32 v[86:87], v[2:3], v[86:87]
	s_nop 0
	v_pk_mul_f32 v[88:89], v[36:37], v[86:87] op_sel_hi:[0,1]
	v_pk_mul_f32 v[86:87], v[36:37], v[90:91] op_sel_hi:[0,1]
	v_add_co_u32_e32 v90, vcc, 0xfffff000, v16
	s_nop 1
	v_addc_co_u32_e32 v91, vcc, -1, v17, vcc
	global_store_dwordx4 v[90:91], v[86:89], off offset:-3072
	s_cbranch_scc1 .LBB0_305
	s_load_dwordx2 s[38:39], s[0:1], 0x98
	v_rsq_f32_e32 v86, v84
	s_lshl_b64 s[40:41], s[50:51], 13
	v_lshlrev_b32_e32 v88, 16, v82
	v_and_b32_e32 v89, 0xffff0000, v82
	v_lshlrev_b32_e32 v82, 16, v83
	v_and_b32_e32 v83, 0xffff0000, v83
	s_waitcnt lgkmcnt(0)
	s_add_u32 s38, s38, s40
	v_pk_mul_f32 v[90:91], v[0:1], v[88:89]
	v_pk_mul_f32 v[82:83], v[2:3], v[82:83]
	s_addc_u32 s39, s39, s41
	v_pk_mul_f32 v[88:89], v[86:87], v[82:83] op_sel_hi:[0,1]
	v_pk_mul_f32 v[86:87], v[86:87], v[90:91] op_sel_hi:[0,1]
	global_store_dwordx4 v192, v[86:89], s[38:39]
; template <class T> __device__ __forceinline__ void gst_nt(void* p, T v) { __builtin_nontemporal_store(v, (GAS T*)p); }
; __device__ __forceinline__ float rstd_of(float ss, float inv_n) { return __builtin_amdgcn_rsqf(ss * inv_n + RMS_EPS); }
; __device__ __forceinline__ float bf_lo(unsigned w) { return __uint_as_float(w << 16); }
; __device__ __forceinline__ float bf_hi(unsigned w) { return __uint_as_float(w & 0xffff0000u); }
; __global__ void __launch_bounds__(NWAVES * 64, 2) mk_fwd(Args args) {
;     ...
;                 for (int j = 0; j < 8; ++j) { const f32x4 g = gld<f32x4>(gr + 64 * j);
; #pragma unroll
;                     for (int q = 0; q < 4; ++q) if (q == 0 || mr[q] != m0) {
;                         const float rs = pg8::rstd_of(ss[q], 1.0f / 2048.0f);
;                         gst_nt<f32x4>((f32x4*)(ka->out + (size_t)mr[q] * D) + lane + 64 * j, (f32x4){bf_lo(r[q][j].x), bf_hi(r[q][j].x), bf_lo(r[q][j].y), bf_hi(r[q][j].y)} * g * rs); }
.LBB0_305:
	s_cmp_lg_u32 s7, s44
	s_cselect_b64 s[38:39], -1, 0
	s_cmp_eq_u32 s7, s44
	v_fmamk_f32 v82, v85, 0x3a000000, v246
	s_cbranch_scc1 .LBB0_307
	s_load_dwordx2 s[40:41], s[0:1], 0x98
	v_rsq_f32_e32 v86, v82
	s_lshl_b64 s[42:43], s[44:45], 13
	v_lshlrev_b32_e32 v88, 16, v80
	v_and_b32_e32 v89, 0xffff0000, v80
	v_lshlrev_b32_e32 v80, 16, v81
	v_and_b32_e32 v81, 0xffff0000, v81
	s_waitcnt lgkmcnt(0)
	s_add_u32 s40, s40, s42
	v_pk_mul_f32 v[90:91], v[0:1], v[88:89]
	v_pk_mul_f32 v[80:81], v[2:3], v[80:81]
	s_addc_u32 s41, s41, s43
	v_pk_mul_f32 v[88:89], v[86:87], v[80:81] op_sel_hi:[0,1]
	v_pk_mul_f32 v[86:87], v[86:87], v[90:91] op_sel_hi:[0,1]
	global_store_dwordx4 v192, v[86:89], s[40:41]
.LBB0_307:
	s_cmp_lg_u32 s7, s2
	s_cselect_b64 s[52:53], -1, 0
	s_cmp_eq_u32 s7, s2
	v_fmamk_f32 v80, v37, 0x3a000000, v246
	s_cbranch_scc1 .LBB0_309
	s_load_dwordx2 s[40:41], s[0:1], 0x98
	v_rsq_f32_e32 v86, v80
	s_lshl_b64 s[42:43], s[2:3], 13
	v_lshlrev_b32_e32 v88, 16, v78
	v_and_b32_e32 v89, 0xffff0000, v78
	v_lshlrev_b32_e32 v78, 16, v79
	v_and_b32_e32 v79, 0xffff0000, v79
	s_waitcnt lgkmcnt(0)
	s_add_u32 s40, s40, s42
	v_pk_mul_f32 v[0:1], v[0:1], v[88:89]
	v_pk_mul_f32 v[2:3], v[2:3], v[78:79]
	s_addc_u32 s41, s41, s43
	v_pk_mul_f32 v[2:3], v[86:87], v[2:3] op_sel_hi:[0,1]
	v_pk_mul_f32 v[0:1], v[86:87], v[0:1] op_sel_hi:[0,1]
	global_store_dwordx4 v192, v[0:3], s[40:41]
.LBB0_309:
	global_load_dwordx4 v[0:3], v[6:7], off offset:1024
	v_lshlrev_b32_e32 v78, 16, v76
	v_and_b32_e32 v79, 0xffff0000, v76
	v_lshlrev_b32_e32 v76, 16, v77
	v_and_b32_e32 v77, 0xffff0000, v77
	v_add_co_u32_e32 v88, vcc, 0xfffff000, v16
	v_mov_b32_e32 v37, v36
	v_mov_b32_e32 v86, v36
	v_mov_b32_e32 v87, v36
	v_cndmask_b32_e64 v81, 0, 1, s[14:15]
	v_addc_co_u32_e32 v89, vcc, -1, v17, vcc
	v_cmp_ne_u32_e64 s[42:43], 1, v81
	s_andn2_b64 vcc, exec, s[14:15]
	s_waitcnt vmcnt(0)
	v_pk_mul_f32 v[90:91], v[0:1], v[78:79]
	v_pk_mul_f32 v[76:77], v[2:3], v[76:77]
	s_nop 0
	v_pk_mul_f32 v[78:79], v[86:87], v[76:77]
	v_pk_mul_f32 v[76:77], v[36:37], v[90:91]
	global_store_dwordx4 v[88:89], v[76:79], off offset:-2048
	s_cbranch_vccnz .LBB0_336
	s_load_dwordx2 s[14:15], s[0:1], 0x98
	v_rsq_f32_e32 v78, v84
	s_lshl_b64 s[40:41], s[50:51], 13
	v_lshlrev_b32_e32 v76, 16, v74
	v_and_b32_e32 v77, 0xffff0000, v74
	v_lshlrev_b32_e32 v74, 16, v75
	v_and_b32_e32 v75, 0xffff0000, v75
	s_waitcnt lgkmcnt(0)
	s_add_u32 s14, s14, s40
	v_pk_mul_f32 v[86:87], v[0:1], v[76:77]
	v_pk_mul_f32 v[74:75], v[2:3], v[74:75]
	s_addc_u32 s15, s15, s41
	v_pk_mul_f32 v[76:77], v[78:79], v[74:75] op_sel_hi:[0,1]
	v_pk_mul_f32 v[74:75], v[78:79], v[86:87] op_sel_hi:[0,1]
	global_store_dwordx4 v192, v[74:77], s[14:15] offset:1024
	s_nop 1
	v_cndmask_b32_e64 v74, 0, 1, s[38:39]
	v_cmp_ne_u32_e64 s[40:41], 1, v74
	s_andn2_b64 vcc, exec, s[38:39]
	s_cbranch_vccz .LBB0_337

; template <class T> __device__ __forceinline__ void gst_nt(void* p, T v) { __builtin_nontemporal_store(v, (GAS T*)p); }
; __device__ __forceinline__ float rstd_of(float ss, float inv_n) { return __builtin_amdgcn_rsqf(ss * inv_n + RMS_EPS); }
; __device__ __forceinline__ float bf_lo(unsigned w) { return __uint_as_float(w << 16); }
; __device__ __forceinline__ float bf_hi(unsigned w) { return __uint_as_float(w & 0xffff0000u); }
; __global__ void __launch_bounds__(NWAVES * 64, 2) mk_fwd(Args args) {
;     ...
;                 for (int j = 0; j < 8; ++j) { const f32x4 g = gld<f32x4>(gr + 64 * j);
; #pragma unroll
;                     for (int q = 0; q < 4; ++q) if (q == 0 || mr[q] != m0) {
;                         const float rs = pg8::rstd_of(ss[q], 1.0f / 2048.0f);
;                         gst_nt<f32x4>((f32x4*)(ka->out + (size_t)mr[q] * D) + lane + 64 * j, (f32x4){bf_lo(r[q][j].x), bf_hi(r[q][j].x), bf_lo(r[q][j].y), bf_hi(r[q][j].y)} * g * rs); }
.LBB0_312:
	s_load_dwordx2 s[14:15], s[0:1], 0x98
	v_rsq_f32_e32 v72, v80
	s_lshl_b64 s[52:53], s[2:3], 13
	v_lshlrev_b32_e32 v74, 16, v70
	v_and_b32_e32 v75, 0xffff0000, v70
	v_lshlrev_b32_e32 v70, 16, v71
	v_and_b32_e32 v71, 0xffff0000, v71
	s_waitcnt lgkmcnt(0)
	s_add_u32 s14, s14, s52
	v_pk_mul_f32 v[0:1], v[0:1], v[74:75]
	v_pk_mul_f32 v[2:3], v[2:3], v[70:71]
	s_addc_u32 s15, s15, s53
	v_pk_mul_f32 v[2:3], v[72:73], v[2:3] op_sel_hi:[0,1]
	v_pk_mul_f32 v[0:1], v[72:73], v[0:1] op_sel_hi:[0,1]
	global_store_dwordx4 v192, v[0:3], s[14:15] offset:1024
.LBB0_313:
	global_load_dwordx4 v[0:3], v[6:7], off offset:2048
	v_lshlrev_b32_e32 v70, 16, v68
	v_and_b32_e32 v71, 0xffff0000, v68
	v_lshlrev_b32_e32 v68, 16, v69
	v_and_b32_e32 v69, 0xffff0000, v69
	s_waitcnt vmcnt(0)
	v_pk_mul_f32 v[72:73], v[0:1], v[70:71]
	v_pk_mul_f32 v[68:69], v[2:3], v[68:69]
	v_mov_b32_e32 v70, v36
	v_mov_b32_e32 v71, v36
	v_pk_mul_f32 v[70:71], v[70:71], v[68:69]
	v_pk_mul_f32 v[68:69], v[36:37], v[72:73]
	v_add_co_u32_e32 v72, vcc, 0xfffff000, v16
	s_nop 1
	v_addc_co_u32_e32 v73, vcc, -1, v17, vcc
	s_and_b64 vcc, exec, s[42:43]
	global_store_dwordx4 v[72:73], v[68:71], off offset:-1024
	s_cbranch_vccnz .LBB0_338
	s_load_dwordx2 s[14:15], s[0:1], 0x98
	v_rsq_f32_e32 v70, v84
	s_lshl_b64 s[52:53], s[50:51], 13
	v_lshlrev_b32_e32 v68, 16, v66
	v_and_b32_e32 v69, 0xffff0000, v66
	v_lshlrev_b32_e32 v66, 16, v67
	v_and_b32_e32 v67, 0xffff0000, v67
	s_waitcnt lgkmcnt(0)
	s_add_u32 s14, s14, s52
	v_pk_mul_f32 v[72:73], v[0:1], v[68:69]
	v_pk_mul_f32 v[66:67], v[2:3], v[66:67]
	s_addc_u32 s15, s15, s53
	v_pk_mul_f32 v[68:69], v[70:71], v[66:67] op_sel_hi:[0,1]
	v_pk_mul_f32 v[66:67], v[70:71], v[72:73] op_sel_hi:[0,1]
	global_store_dwordx4 v192, v[66:69], s[14:15] offset:2048
	s_and_b64 vcc, exec, s[40:41]
	s_cbranch_vccz .LBB0_339

; template <class T> __device__ __forceinline__ void gst_nt(void* p, T v) { __builtin_nontemporal_store(v, (GAS T*)p); }
; __device__ __forceinline__ float rstd_of(float ss, float inv_n) { return __builtin_amdgcn_rsqf(ss * inv_n + RMS_EPS); }
; __device__ __forceinline__ float bf_lo(unsigned w) { return __uint_as_float(w << 16); }
; __device__ __forceinline__ float bf_hi(unsigned w) { return __uint_as_float(w & 0xffff0000u); }
; __global__ void __launch_bounds__(NWAVES * 64, 2) mk_fwd(Args args) {
;     ...
;                 for (int j = 0; j < 8; ++j) { const f32x4 g = gld<f32x4>(gr + 64 * j);
; #pragma unroll
;                     for (int q = 0; q < 4; ++q) if (q == 0 || mr[q] != m0) {
;                         const float rs = pg8::rstd_of(ss[q], 1.0f / 2048.0f);
;                         gst_nt<f32x4>((f32x4*)(ka->out + (size_t)mr[q] * D) + lane + 64 * j, (f32x4){bf_lo(r[q][j].x), bf_hi(r[q][j].x), bf_lo(r[q][j].y), bf_hi(r[q][j].y)} * g * rs); }
.LBB0_316:
	s_load_dwordx2 s[14:15], s[0:1], 0x98
	v_rsq_f32_e32 v64, v80
	s_lshl_b64 s[52:53], s[2:3], 13
	v_lshlrev_b32_e32 v66, 16, v62
	v_and_b32_e32 v67, 0xffff0000, v62
	v_lshlrev_b32_e32 v62, 16, v63
	v_and_b32_e32 v63, 0xffff0000, v63
	s_waitcnt lgkmcnt(0)
	s_add_u32 s14, s14, s52
	v_pk_mul_f32 v[0:1], v[0:1], v[66:67]
	v_pk_mul_f32 v[2:3], v[2:3], v[62:63]
	s_addc_u32 s15, s15, s53
	v_pk_mul_f32 v[2:3], v[64:65], v[2:3] op_sel_hi:[0,1]
	v_pk_mul_f32 v[0:1], v[64:65], v[0:1] op_sel_hi:[0,1]
	global_store_dwordx4 v192, v[0:3], s[14:15] offset:2048
.LBB0_317:
	global_load_dwordx4 v[0:3], v[6:7], off offset:3072
	v_lshlrev_b32_e32 v62, 16, v60
	v_and_b32_e32 v63, 0xffff0000, v60
	v_lshlrev_b32_e32 v60, 16, v61
	v_and_b32_e32 v61, 0xffff0000, v61
	v_mov_b32_e32 v64, v36
	v_mov_b32_e32 v65, v36
	s_and_b64 vcc, exec, s[42:43]
	s_waitcnt vmcnt(0)
	v_pk_mul_f32 v[66:67], v[0:1], v[62:63]
	v_pk_mul_f32 v[60:61], v[2:3], v[60:61]
	s_nop 0
	v_pk_mul_f32 v[62:63], v[64:65], v[60:61]
	v_pk_mul_f32 v[60:61], v[36:37], v[66:67]
	global_store_dwordx4 v[16:17], v[60:63], off offset:-4096
	s_cbranch_vccnz .LBB0_340
	s_load_dwordx2 s[14:15], s[0:1], 0x98
	v_rsq_f32_e32 v62, v84
	s_lshl_b64 s[52:53], s[50:51], 13
	v_lshlrev_b32_e32 v60, 16, v58
	v_and_b32_e32 v61, 0xffff0000, v58
	v_lshlrev_b32_e32 v58, 16, v59
	v_and_b32_e32 v59, 0xffff0000, v59
	s_waitcnt lgkmcnt(0)
	s_add_u32 s14, s14, s52
	v_pk_mul_f32 v[64:65], v[0:1], v[60:61]
	v_pk_mul_f32 v[58:59], v[2:3], v[58:59]
	s_addc_u32 s15, s15, s53
	v_pk_mul_f32 v[60:61], v[62:63], v[58:59] op_sel_hi:[0,1]
	v_pk_mul_f32 v[58:59], v[62:63], v[64:65] op_sel_hi:[0,1]
	global_store_dwordx4 v192, v[58:61], s[14:15] offset:3072
	s_and_b64 vcc, exec, s[40:41]
	s_cbranch_vccz .LBB0_341

; template <class T> __device__ __forceinline__ void gst_nt(void* p, T v) { __builtin_nontemporal_store(v, (GAS T*)p); }
; __device__ __forceinline__ float rstd_of(float ss, float inv_n) { return __builtin_amdgcn_rsqf(ss * inv_n + RMS_EPS); }
; __device__ __forceinline__ float bf_lo(unsigned w) { return __uint_as_float(w << 16); }
; __device__ __forceinline__ float bf_hi(unsigned w) { return __uint_as_float(w & 0xffff0000u); }
; __global__ void __launch_bounds__(NWAVES * 64, 2) mk_fwd(Args args) {
;     ...
;                 for (int j = 0; j < 8; ++j) { const f32x4 g = gld<f32x4>(gr + 64 * j);
; #pragma unroll
;                     for (int q = 0; q < 4; ++q) if (q == 0 || mr[q] != m0) {
;                         const float rs = pg8::rstd_of(ss[q], 1.0f / 2048.0f);
;                         gst_nt<f32x4>((f32x4*)(ka->out + (size_t)mr[q] * D) + lane + 64 * j, (f32x4){bf_lo(r[q][j].x), bf_hi(r[q][j].x), bf_lo(r[q][j].y), bf_hi(r[q][j].y)} * g * rs); }
.LBB0_320:
	s_load_dwordx2 s[14:15], s[0:1], 0x98
	v_rsq_f32_e32 v56, v80
	s_lshl_b64 s[52:53], s[2:3], 13
	v_lshlrev_b32_e32 v58, 16, v54
	v_and_b32_e32 v59, 0xffff0000, v54
	v_lshlrev_b32_e32 v54, 16, v55
	v_and_b32_e32 v55, 0xffff0000, v55
	s_waitcnt lgkmcnt(0)
	s_add_u32 s14, s14, s52
	v_pk_mul_f32 v[0:1], v[0:1], v[58:59]
	v_pk_mul_f32 v[2:3], v[2:3], v[54:55]
	s_addc_u32 s15, s15, s53
	v_pk_mul_f32 v[2:3], v[56:57], v[2:3] op_sel_hi:[0,1]
	v_pk_mul_f32 v[0:1], v[56:57], v[0:1] op_sel_hi:[0,1]
	global_store_dwordx4 v192, v[0:3], s[14:15] offset:3072
.LBB0_321:
	global_load_dwordx4 v[0:3], v[8:9], off
	v_lshlrev_b32_e32 v54, 16, v52
	v_and_b32_e32 v55, 0xffff0000, v52
	v_lshlrev_b32_e32 v52, 16, v53
	v_and_b32_e32 v53, 0xffff0000, v53
	v_mov_b32_e32 v56, v36
	v_mov_b32_e32 v57, v36
	s_and_b64 vcc, exec, s[42:43]
	s_waitcnt vmcnt(0)
	v_pk_mul_f32 v[58:59], v[0:1], v[54:55]
	v_pk_mul_f32 v[52:53], v[2:3], v[52:53]
	s_nop 0
	v_pk_mul_f32 v[54:55], v[56:57], v[52:53]
	v_pk_mul_f32 v[52:53], v[36:37], v[58:59]
	global_store_dwordx4 v[16:17], v[52:55], off offset:-3072
	s_cbranch_vccnz .LBB0_342
	s_load_dwordx2 s[14:15], s[0:1], 0x98
	v_rsq_f32_e32 v54, v84
	s_lshl_b64 s[52:53], s[50:51], 13
	v_lshlrev_b32_e32 v52, 16, v50
	v_and_b32_e32 v53, 0xffff0000, v50
	s_waitcnt lgkmcnt(0)
	s_add_u32 s14, s14, s52
	s_addc_u32 s15, s15, s53
	v_lshlrev_b32_e32 v50, 16, v51
	v_and_b32_e32 v51, 0xffff0000, v51
	v_lshl_add_u64 v[56:57], s[14:15], 0, v[192:193]
	v_pk_mul_f32 v[58:59], v[0:1], v[52:53]
	v_pk_mul_f32 v[50:51], v[2:3], v[50:51]
	s_nop 0
	v_pk_mul_f32 v[52:53], v[54:55], v[50:51] op_sel_hi:[0,1]
	v_pk_mul_f32 v[50:51], v[54:55], v[58:59] op_sel_hi:[0,1]
	v_add_co_u32_e32 v54, vcc, 0x1000, v56
	s_nop 1
	v_addc_co_u32_e32 v55, vcc, 0, v57, vcc
	global_store_dwordx4 v[54:55], v[50:53], off
	s_and_b64 vcc, exec, s[40:41]
	s_cbranch_vccz .LBB0_343

; template <class T> __device__ __forceinline__ void gst_nt(void* p, T v) { __builtin_nontemporal_store(v, (GAS T*)p); }
; __device__ __forceinline__ float rstd_of(float ss, float inv_n) { return __builtin_amdgcn_rsqf(ss * inv_n + RMS_EPS); }
; __device__ __forceinline__ float bf_lo(unsigned w) { return __uint_as_float(w << 16); }
; __device__ __forceinline__ float bf_hi(unsigned w) { return __uint_as_float(w & 0xffff0000u); }
; __global__ void __launch_bounds__(NWAVES * 64, 2) mk_fwd(Args args) {
;     ...
;                 for (int j = 0; j < 8; ++j) { const f32x4 g = gld<f32x4>(gr + 64 * j);
; #pragma unroll
;                     for (int q = 0; q < 4; ++q) if (q == 0 || mr[q] != m0) {
;                         const float rs = pg8::rstd_of(ss[q], 1.0f / 2048.0f);
;                         gst_nt<f32x4>((f32x4*)(ka->out + (size_t)mr[q] * D) + lane + 64 * j, (f32x4){bf_lo(r[q][j].x), bf_hi(r[q][j].x), bf_lo(r[q][j].y), bf_hi(r[q][j].y)} * g * rs); }
.LBB0_324:
	s_load_dwordx2 s[14:15], s[0:1], 0x98
	s_lshl_b64 s[52:53], s[2:3], 13
	v_rsq_f32_e32 v48, v80
	v_lshlrev_b32_e32 v50, 16, v46
	v_and_b32_e32 v51, 0xffff0000, v46
	s_waitcnt lgkmcnt(0)
	s_add_u32 s14, s14, s52
	s_addc_u32 s15, s15, s53
	v_lshl_add_u64 v[52:53], s[14:15], 0, v[192:193]
	v_lshlrev_b32_e32 v46, 16, v47
	v_and_b32_e32 v47, 0xffff0000, v47
	v_pk_mul_f32 v[0:1], v[0:1], v[50:51]
	v_pk_mul_f32 v[2:3], v[2:3], v[46:47]
	v_add_co_u32_e32 v46, vcc, 0x1000, v52
	v_pk_mul_f32 v[2:3], v[48:49], v[2:3] op_sel_hi:[0,1]
	v_pk_mul_f32 v[0:1], v[48:49], v[0:1] op_sel_hi:[0,1]
	v_addc_co_u32_e32 v47, vcc, 0, v53, vcc
	global_store_dwordx4 v[46:47], v[0:3], off
.LBB0_325:
	global_load_dwordx4 v[0:3], v[10:11], off
	v_lshlrev_b32_e32 v46, 16, v44
	v_and_b32_e32 v47, 0xffff0000, v44
	v_lshlrev_b32_e32 v44, 16, v45
	v_and_b32_e32 v45, 0xffff0000, v45
	v_mov_b32_e32 v48, v36
	v_mov_b32_e32 v49, v36
	s_and_b64 vcc, exec, s[42:43]
	s_waitcnt vmcnt(0)
	v_pk_mul_f32 v[50:51], v[0:1], v[46:47]
	v_pk_mul_f32 v[44:45], v[2:3], v[44:45]
	s_nop 0
	v_pk_mul_f32 v[46:47], v[48:49], v[44:45]
	v_pk_mul_f32 v[44:45], v[36:37], v[50:51]
	global_store_dwordx4 v[16:17], v[44:47], off offset:-2048
	s_cbranch_vccnz .LBB0_344
	s_load_dwordx2 s[14:15], s[0:1], 0x98
	v_rsq_f32_e32 v46, v84
	s_lshl_b64 s[52:53], s[50:51], 13
	v_lshlrev_b32_e32 v44, 16, v42
	v_and_b32_e32 v45, 0xffff0000, v42
	s_waitcnt lgkmcnt(0)
	s_add_u32 s14, s14, s52
	s_addc_u32 s15, s15, s53
	v_lshlrev_b32_e32 v42, 16, v43
	v_and_b32_e32 v43, 0xffff0000, v43
	v_lshl_add_u64 v[48:49], s[14:15], 0, v[192:193]
	v_pk_mul_f32 v[50:51], v[0:1], v[44:45]
	v_pk_mul_f32 v[42:43], v[2:3], v[42:43]
	s_nop 0
	v_pk_mul_f32 v[44:45], v[46:47], v[42:43] op_sel_hi:[0,1]
	v_pk_mul_f32 v[42:43], v[46:47], v[50:51] op_sel_hi:[0,1]
	v_add_co_u32_e32 v46, vcc, 0x1000, v48
	s_nop 1
	v_addc_co_u32_e32 v47, vcc, 0, v49, vcc
	global_store_dwordx4 v[46:47], v[42:45], off offset:1024
	s_and_b64 vcc, exec, s[40:41]
	s_cbranch_vccz .LBB0_345

; template <class T> __device__ __forceinline__ void gst_nt(void* p, T v) { __builtin_nontemporal_store(v, (GAS T*)p); }
; __device__ __forceinline__ float rstd_of(float ss, float inv_n) { return __builtin_amdgcn_rsqf(ss * inv_n + RMS_EPS); }
; __device__ __forceinline__ float bf_lo(unsigned w) { return __uint_as_float(w << 16); }
; __device__ __forceinline__ float bf_hi(unsigned w) { return __uint_as_float(w & 0xffff0000u); }
; __global__ void __launch_bounds__(NWAVES * 64, 2) mk_fwd(Args args) {
;     ...
;                 for (int j = 0; j < 8; ++j) { const f32x4 g = gld<f32x4>(gr + 64 * j);
; #pragma unroll
;                     for (int q = 0; q < 4; ++q) if (q == 0 || mr[q] != m0) {
;                         const float rs = pg8::rstd_of(ss[q], 1.0f / 2048.0f);
;                         gst_nt<f32x4>((f32x4*)(ka->out + (size_t)mr[q] * D) + lane + 64 * j, (f32x4){bf_lo(r[q][j].x), bf_hi(r[q][j].x), bf_lo(r[q][j].y), bf_hi(r[q][j].y)} * g * rs); }
.LBB0_328:
	s_load_dwordx2 s[14:15], s[0:1], 0x98
	s_lshl_b64 s[52:53], s[2:3], 13
	v_rsq_f32_e32 v40, v80
	v_lshlrev_b32_e32 v42, 16, v38
	v_and_b32_e32 v43, 0xffff0000, v38
	s_waitcnt lgkmcnt(0)
	s_add_u32 s14, s14, s52
	s_addc_u32 s15, s15, s53
	v_lshl_add_u64 v[44:45], s[14:15], 0, v[192:193]
	v_lshlrev_b32_e32 v38, 16, v39
	v_and_b32_e32 v39, 0xffff0000, v39
	v_pk_mul_f32 v[0:1], v[0:1], v[42:43]
	v_pk_mul_f32 v[2:3], v[2:3], v[38:39]
	v_add_co_u32_e32 v38, vcc, 0x1000, v44
	v_pk_mul_f32 v[2:3], v[40:41], v[2:3] op_sel_hi:[0,1]
	v_pk_mul_f32 v[0:1], v[40:41], v[0:1] op_sel_hi:[0,1]
	v_addc_co_u32_e32 v39, vcc, 0, v45, vcc
	global_store_dwordx4 v[38:39], v[0:3], off offset:1024
.LBB0_329:
	global_load_dwordx4 v[0:3], v[12:13], off
	v_lshlrev_b32_e32 v38, 16, v34
	v_and_b32_e32 v39, 0xffff0000, v34
	v_lshlrev_b32_e32 v34, 16, v35
	v_and_b32_e32 v35, 0xffff0000, v35
	v_mov_b32_e32 v40, v36
	v_mov_b32_e32 v41, v36
	s_and_b64 vcc, exec, s[42:43]
	s_waitcnt vmcnt(0)
	v_pk_mul_f32 v[38:39], v[0:1], v[38:39]
	v_pk_mul_f32 v[34:35], v[2:3], v[34:35]
	v_pk_mul_f32 v[38:39], v[36:37], v[38:39]
	v_pk_mul_f32 v[40:41], v[40:41], v[34:35]
	global_store_dwordx4 v[16:17], v[38:41], off offset:-1024
	s_cbranch_vccnz .LBB0_346
	s_load_dwordx2 s[14:15], s[0:1], 0x98
	v_rsq_f32_e32 v38, v84
	s_lshl_b64 s[52:53], s[50:51], 13
	v_lshlrev_b32_e32 v34, 16, v32
	v_and_b32_e32 v35, 0xffff0000, v32
	s_waitcnt lgkmcnt(0)
	s_add_u32 s14, s14, s52
	s_addc_u32 s15, s15, s53
	v_lshlrev_b32_e32 v32, 16, v33
	v_and_b32_e32 v33, 0xffff0000, v33
	v_lshl_add_u64 v[40:41], s[14:15], 0, v[192:193]
	v_pk_mul_f32 v[42:43], v[0:1], v[34:35]
	v_pk_mul_f32 v[32:33], v[2:3], v[32:33]
	s_nop 0
	v_pk_mul_f32 v[34:35], v[38:39], v[32:33] op_sel_hi:[0,1]
	v_pk_mul_f32 v[32:33], v[38:39], v[42:43] op_sel_hi:[0,1]
	v_add_co_u32_e32 v38, vcc, 0x1000, v40
	s_nop 1
	v_addc_co_u32_e32 v39, vcc, 0, v41, vcc
	global_store_dwordx4 v[38:39], v[32:35], off offset:2048
	s_and_b64 vcc, exec, s[40:41]
	s_cbranch_vccz .LBB0_347

; template <class T> __device__ __forceinline__ void gst_nt(void* p, T v) { __builtin_nontemporal_store(v, (GAS T*)p); }
; __device__ __forceinline__ float rstd_of(float ss, float inv_n) { return __builtin_amdgcn_rsqf(ss * inv_n + RMS_EPS); }
; __device__ __forceinline__ float bf_lo(unsigned w) { return __uint_as_float(w << 16); }
; __device__ __forceinline__ float bf_hi(unsigned w) { return __uint_as_float(w & 0xffff0000u); }
; __global__ void __launch_bounds__(NWAVES * 64, 2) mk_fwd(Args args) {
;     ...
;                 for (int j = 0; j < 8; ++j) { const f32x4 g = gld<f32x4>(gr + 64 * j);
; #pragma unroll
;                     for (int q = 0; q < 4; ++q) if (q == 0 || mr[q] != m0) {
;                         const float rs = pg8::rstd_of(ss[q], 1.0f / 2048.0f);
;                         gst_nt<f32x4>((f32x4*)(ka->out + (size_t)mr[q] * D) + lane + 64 * j, (f32x4){bf_lo(r[q][j].x), bf_hi(r[q][j].x), bf_lo(r[q][j].y), bf_hi(r[q][j].y)} * g * rs); }
.LBB0_332:
	s_load_dwordx2 s[14:15], s[0:1], 0x98
	s_lshl_b64 s[52:53], s[2:3], 13
	v_rsq_f32_e32 v30, v80
	v_lshlrev_b32_e32 v32, 16, v28
	v_and_b32_e32 v33, 0xffff0000, v28
	s_waitcnt lgkmcnt(0)
	s_add_u32 s14, s14, s52
	s_addc_u32 s15, s15, s53
	v_lshl_add_u64 v[34:35], s[14:15], 0, v[192:193]
	v_lshlrev_b32_e32 v28, 16, v29
	v_and_b32_e32 v29, 0xffff0000, v29
	v_pk_mul_f32 v[0:1], v[0:1], v[32:33]
	v_pk_mul_f32 v[2:3], v[2:3], v[28:29]
	v_add_co_u32_e32 v28, vcc, 0x1000, v34
	v_pk_mul_f32 v[2:3], v[30:31], v[2:3] op_sel_hi:[0,1]
	v_pk_mul_f32 v[0:1], v[30:31], v[0:1] op_sel_hi:[0,1]
	v_addc_co_u32_e32 v29, vcc, 0, v35, vcc
	global_store_dwordx4 v[28:29], v[0:3], off offset:2048
.LBB0_333:
	global_load_dwordx4 v[0:3], v[14:15], off
	v_lshlrev_b32_e32 v28, 16, v26
	v_and_b32_e32 v29, 0xffff0000, v26
	v_lshlrev_b32_e32 v26, 16, v27
	v_and_b32_e32 v27, 0xffff0000, v27
	v_mov_b32_e32 v30, v36
	v_mov_b32_e32 v31, v36
	s_and_b64 vcc, exec, s[42:43]
	s_waitcnt vmcnt(0)
	v_pk_mul_f32 v[32:33], v[0:1], v[28:29]
	v_pk_mul_f32 v[26:27], v[2:3], v[26:27]
	s_nop 0
	v_pk_mul_f32 v[28:29], v[30:31], v[26:27]
	v_pk_mul_f32 v[26:27], v[36:37], v[32:33]
	global_store_dwordx4 v[16:17], v[26:29], off
	s_cbranch_vccnz .LBB0_348
	s_load_dwordx2 s[14:15], s[0:1], 0x98
	v_rsq_f32_e32 v28, v84
	s_lshl_b64 s[42:43], s[50:51], 13
	v_lshlrev_b32_e32 v26, 16, v24
	v_and_b32_e32 v27, 0xffff0000, v24
	s_waitcnt lgkmcnt(0)
	s_add_u32 s14, s14, s42
	s_addc_u32 s15, s15, s43
	v_lshlrev_b32_e32 v24, 16, v25
	v_and_b32_e32 v25, 0xffff0000, v25
	v_lshl_add_u64 v[30:31], s[14:15], 0, v[192:193]
	v_pk_mul_f32 v[32:33], v[0:1], v[26:27]
	v_pk_mul_f32 v[24:25], v[2:3], v[24:25]
	s_nop 0
	v_pk_mul_f32 v[26:27], v[28:29], v[24:25] op_sel_hi:[0,1]
	v_pk_mul_f32 v[24:25], v[28:29], v[32:33] op_sel_hi:[0,1]
	v_add_co_u32_e32 v28, vcc, 0x1000, v30
	s_nop 1
	v_addc_co_u32_e32 v29, vcc, 0, v31, vcc
	global_store_dwordx4 v[28:29], v[24:27], off offset:3072
	s_and_b64 vcc, exec, s[40:41]
	s_cbranch_vccz .LBB0_349

; template <class T> __device__ __forceinline__ void gst_nt(void* p, T v) { __builtin_nontemporal_store(v, (GAS T*)p); }
; __device__ __forceinline__ float rstd_of(float ss, float inv_n) { return __builtin_amdgcn_rsqf(ss * inv_n + RMS_EPS); }
; __device__ __forceinline__ float bf_lo(unsigned w) { return __uint_as_float(w << 16); }
; __device__ __forceinline__ float bf_hi(unsigned w) { return __uint_as_float(w & 0xffff0000u); }
; __global__ void __launch_bounds__(NWAVES * 64, 2) mk_fwd(Args args) {
;     ...
;                 for (int j = 0; j < 8; ++j) { const f32x4 g = gld<f32x4>(gr + 64 * j);
; #pragma unroll
;                     for (int q = 0; q < 4; ++q) if (q == 0 || mr[q] != m0) {
;                         const float rs = pg8::rstd_of(ss[q], 1.0f / 2048.0f);
;                         gst_nt<f32x4>((f32x4*)(ka->out + (size_t)mr[q] * D) + lane + 64 * j, (f32x4){bf_lo(r[q][j].x), bf_hi(r[q][j].x), bf_lo(r[q][j].y), bf_hi(r[q][j].y)} * g * rs); }
.LBB0_337:
	s_load_dwordx2 s[14:15], s[0:1], 0x98
	v_rsq_f32_e32 v76, v82
	s_lshl_b64 s[38:39], s[44:45], 13
	v_lshlrev_b32_e32 v74, 16, v72
	v_and_b32_e32 v75, 0xffff0000, v72
	v_lshlrev_b32_e32 v72, 16, v73
	v_and_b32_e32 v73, 0xffff0000, v73
	s_waitcnt lgkmcnt(0)
	s_add_u32 s14, s14, s38
	v_pk_mul_f32 v[78:79], v[0:1], v[74:75]
	v_pk_mul_f32 v[72:73], v[2:3], v[72:73]
	s_addc_u32 s15, s15, s39
	v_pk_mul_f32 v[74:75], v[76:77], v[72:73] op_sel_hi:[0,1]
	v_pk_mul_f32 v[72:73], v[76:77], v[78:79] op_sel_hi:[0,1]
	global_store_dwordx4 v192, v[72:75], s[14:15] offset:1024
	s_nop 1
	v_cndmask_b32_e64 v72, 0, 1, s[52:53]
	v_cmp_ne_u32_e64 s[38:39], 1, v72
	s_andn2_b64 vcc, exec, s[52:53]
	s_cbranch_vccz .LBB0_312
	s_branch .LBB0_313

; template <class T> __device__ __forceinline__ void gst_nt(void* p, T v) { __builtin_nontemporal_store(v, (GAS T*)p); }
; __device__ __forceinline__ float rstd_of(float ss, float inv_n) { return __builtin_amdgcn_rsqf(ss * inv_n + RMS_EPS); }
; __device__ __forceinline__ float bf_lo(unsigned w) { return __uint_as_float(w << 16); }
; __device__ __forceinline__ float bf_hi(unsigned w) { return __uint_as_float(w & 0xffff0000u); }
; __global__ void __launch_bounds__(NWAVES * 64, 2) mk_fwd(Args args) {
;     ...
;                 for (int j = 0; j < 8; ++j) { const f32x4 g = gld<f32x4>(gr + 64 * j);
; #pragma unroll
;                     for (int q = 0; q < 4; ++q) if (q == 0 || mr[q] != m0) {
;                         const float rs = pg8::rstd_of(ss[q], 1.0f / 2048.0f);
;                         gst_nt<f32x4>((f32x4*)(ka->out + (size_t)mr[q] * D) + lane + 64 * j, (f32x4){bf_lo(r[q][j].x), bf_hi(r[q][j].x), bf_lo(r[q][j].y), bf_hi(r[q][j].y)} * g * rs); }
.LBB0_339:
	s_load_dwordx2 s[14:15], s[0:1], 0x98
	v_rsq_f32_e32 v68, v82
	s_lshl_b64 s[52:53], s[44:45], 13
	v_lshlrev_b32_e32 v66, 16, v64
	v_and_b32_e32 v67, 0xffff0000, v64
	v_lshlrev_b32_e32 v64, 16, v65
	v_and_b32_e32 v65, 0xffff0000, v65
	s_waitcnt lgkmcnt(0)
	s_add_u32 s14, s14, s52
	v_pk_mul_f32 v[70:71], v[0:1], v[66:67]
	v_pk_mul_f32 v[64:65], v[2:3], v[64:65]
	s_addc_u32 s15, s15, s53
	v_pk_mul_f32 v[66:67], v[68:69], v[64:65] op_sel_hi:[0,1]
	v_pk_mul_f32 v[64:65], v[68:69], v[70:71] op_sel_hi:[0,1]
	global_store_dwordx4 v192, v[64:67], s[14:15] offset:2048
	s_and_b64 vcc, exec, s[38:39]
	s_cbranch_vccz .LBB0_316
	s_branch .LBB0_317

; template <class T> __device__ __forceinline__ void gst_nt(void* p, T v) { __builtin_nontemporal_store(v, (GAS T*)p); }
; __device__ __forceinline__ float rstd_of(float ss, float inv_n) { return __builtin_amdgcn_rsqf(ss * inv_n + RMS_EPS); }
; __device__ __forceinline__ float bf_lo(unsigned w) { return __uint_as_float(w << 16); }
; __device__ __forceinline__ float bf_hi(unsigned w) { return __uint_as_float(w & 0xffff0000u); }
; __global__ void __launch_bounds__(NWAVES * 64, 2) mk_fwd(Args args) {
;     ...
;                 for (int j = 0; j < 8; ++j) { const f32x4 g = gld<f32x4>(gr + 64 * j);
; #pragma unroll
;                     for (int q = 0; q < 4; ++q) if (q == 0 || mr[q] != m0) {
;                         const float rs = pg8::rstd_of(ss[q], 1.0f / 2048.0f);
;                         gst_nt<f32x4>((f32x4*)(ka->out + (size_t)mr[q] * D) + lane + 64 * j, (f32x4){bf_lo(r[q][j].x), bf_hi(r[q][j].x), bf_lo(r[q][j].y), bf_hi(r[q][j].y)} * g * rs); }
.LBB0_341:
	s_load_dwordx2 s[14:15], s[0:1], 0x98
	v_rsq_f32_e32 v60, v82
	s_lshl_b64 s[52:53], s[44:45], 13
	v_lshlrev_b32_e32 v58, 16, v56
	v_and_b32_e32 v59, 0xffff0000, v56
	v_lshlrev_b32_e32 v56, 16, v57
	v_and_b32_e32 v57, 0xffff0000, v57
	s_waitcnt lgkmcnt(0)
	s_add_u32 s14, s14, s52
	v_pk_mul_f32 v[62:63], v[0:1], v[58:59]
	v_pk_mul_f32 v[56:57], v[2:3], v[56:57]
	s_addc_u32 s15, s15, s53
	v_pk_mul_f32 v[58:59], v[60:61], v[56:57] op_sel_hi:[0,1]
	v_pk_mul_f32 v[56:57], v[60:61], v[62:63] op_sel_hi:[0,1]
	global_store_dwordx4 v192, v[56:59], s[14:15] offset:3072
	s_and_b64 vcc, exec, s[38:39]
	s_cbranch_vccz .LBB0_320
	s_branch .LBB0_321

; template <class T> __device__ __forceinline__ void gst_nt(void* p, T v) { __builtin_nontemporal_store(v, (GAS T*)p); }
; __device__ __forceinline__ float rstd_of(float ss, float inv_n) { return __builtin_amdgcn_rsqf(ss * inv_n + RMS_EPS); }
; __device__ __forceinline__ float bf_lo(unsigned w) { return __uint_as_float(w << 16); }
; __device__ __forceinline__ float bf_hi(unsigned w) { return __uint_as_float(w & 0xffff0000u); }
; __global__ void __launch_bounds__(NWAVES * 64, 2) mk_fwd(Args args) {
;     ...
;                 for (int j = 0; j < 8; ++j) { const f32x4 g = gld<f32x4>(gr + 64 * j);
; #pragma unroll
;                     for (int q = 0; q < 4; ++q) if (q == 0 || mr[q] != m0) {
;                         const float rs = pg8::rstd_of(ss[q], 1.0f / 2048.0f);
;                         gst_nt<f32x4>((f32x4*)(ka->out + (size_t)mr[q] * D) + lane + 64 * j, (f32x4){bf_lo(r[q][j].x), bf_hi(r[q][j].x), bf_lo(r[q][j].y), bf_hi(r[q][j].y)} * g * rs); }
.LBB0_343:
	s_load_dwordx2 s[14:15], s[0:1], 0x98
	v_rsq_f32_e32 v52, v82
	s_lshl_b64 s[52:53], s[44:45], 13
	v_lshlrev_b32_e32 v50, 16, v48
	v_and_b32_e32 v51, 0xffff0000, v48
	s_waitcnt lgkmcnt(0)
	s_add_u32 s14, s14, s52
	s_addc_u32 s15, s15, s53
	v_lshlrev_b32_e32 v48, 16, v49
	v_and_b32_e32 v49, 0xffff0000, v49
	v_lshl_add_u64 v[54:55], s[14:15], 0, v[192:193]
	v_pk_mul_f32 v[56:57], v[0:1], v[50:51]
	v_pk_mul_f32 v[48:49], v[2:3], v[48:49]
	s_nop 0
	v_pk_mul_f32 v[50:51], v[52:53], v[48:49] op_sel_hi:[0,1]
	v_pk_mul_f32 v[48:49], v[52:53], v[56:57] op_sel_hi:[0,1]
	v_add_co_u32_e32 v52, vcc, 0x1000, v54
	s_nop 1
	v_addc_co_u32_e32 v53, vcc, 0, v55, vcc
	global_store_dwordx4 v[52:53], v[48:51], off
	s_and_b64 vcc, exec, s[38:39]
	s_cbranch_vccz .LBB0_324
	s_branch .LBB0_325

; template <class T> __device__ __forceinline__ void gst_nt(void* p, T v) { __builtin_nontemporal_store(v, (GAS T*)p); }
; __device__ __forceinline__ float rstd_of(float ss, float inv_n) { return __builtin_amdgcn_rsqf(ss * inv_n + RMS_EPS); }
; __device__ __forceinline__ float bf_lo(unsigned w) { return __uint_as_float(w << 16); }
; __device__ __forceinline__ float bf_hi(unsigned w) { return __uint_as_float(w & 0xffff0000u); }
; __global__ void __launch_bounds__(NWAVES * 64, 2) mk_fwd(Args args) {
;     ...
;                 for (int j = 0; j < 8; ++j) { const f32x4 g = gld<f32x4>(gr + 64 * j);
; #pragma unroll
;                     for (int q = 0; q < 4; ++q) if (q == 0 || mr[q] != m0) {
;                         const float rs = pg8::rstd_of(ss[q], 1.0f / 2048.0f);
;                         gst_nt<f32x4>((f32x4*)(ka->out + (size_t)mr[q] * D) + lane + 64 * j, (f32x4){bf_lo(r[q][j].x), bf_hi(r[q][j].x), bf_lo(r[q][j].y), bf_hi(r[q][j].y)} * g * rs); }
.LBB0_345:
	s_load_dwordx2 s[14:15], s[0:1], 0x98
	v_rsq_f32_e32 v44, v82
	s_lshl_b64 s[52:53], s[44:45], 13
	v_lshlrev_b32_e32 v42, 16, v40
	v_and_b32_e32 v43, 0xffff0000, v40
	s_waitcnt lgkmcnt(0)
	s_add_u32 s14, s14, s52
	s_addc_u32 s15, s15, s53
	v_lshlrev_b32_e32 v40, 16, v41
	v_and_b32_e32 v41, 0xffff0000, v41
	v_lshl_add_u64 v[46:47], s[14:15], 0, v[192:193]
	v_pk_mul_f32 v[48:49], v[0:1], v[42:43]
	v_pk_mul_f32 v[40:41], v[2:3], v[40:41]
	s_nop 0
	v_pk_mul_f32 v[42:43], v[44:45], v[40:41] op_sel_hi:[0,1]
	v_pk_mul_f32 v[40:41], v[44:45], v[48:49] op_sel_hi:[0,1]
	v_add_co_u32_e32 v44, vcc, 0x1000, v46
	s_nop 1
	v_addc_co_u32_e32 v45, vcc, 0, v47, vcc
	global_store_dwordx4 v[44:45], v[40:43], off offset:1024
	s_and_b64 vcc, exec, s[38:39]
	s_cbranch_vccz .LBB0_328
	s_branch .LBB0_329

; template <class T> __device__ __forceinline__ void gst_nt(void* p, T v) { __builtin_nontemporal_store(v, (GAS T*)p); }
; __device__ __forceinline__ float rstd_of(float ss, float inv_n) { return __builtin_amdgcn_rsqf(ss * inv_n + RMS_EPS); }
; __device__ __forceinline__ float bf_lo(unsigned w) { return __uint_as_float(w << 16); }
; __device__ __forceinline__ float bf_hi(unsigned w) { return __uint_as_float(w & 0xffff0000u); }
; __global__ void __launch_bounds__(NWAVES * 64, 2) mk_fwd(Args args) {
;     ...
;                 for (int j = 0; j < 8; ++j) { const f32x4 g = gld<f32x4>(gr + 64 * j);
; #pragma unroll
;                     for (int q = 0; q < 4; ++q) if (q == 0 || mr[q] != m0) {
;                         const float rs = pg8::rstd_of(ss[q], 1.0f / 2048.0f);
;                         gst_nt<f32x4>((f32x4*)(ka->out + (size_t)mr[q] * D) + lane + 64 * j, (f32x4){bf_lo(r[q][j].x), bf_hi(r[q][j].x), bf_lo(r[q][j].y), bf_hi(r[q][j].y)} * g * rs); }
.LBB0_347:
	s_load_dwordx2 s[14:15], s[0:1], 0x98
	v_rsq_f32_e32 v34, v82
	s_lshl_b64 s[52:53], s[44:45], 13
	v_lshlrev_b32_e32 v32, 16, v30
	v_and_b32_e32 v33, 0xffff0000, v30
	s_waitcnt lgkmcnt(0)
	s_add_u32 s14, s14, s52
	s_addc_u32 s15, s15, s53
	v_lshlrev_b32_e32 v30, 16, v31
	v_and_b32_e32 v31, 0xffff0000, v31
	v_lshl_add_u64 v[38:39], s[14:15], 0, v[192:193]
	v_pk_mul_f32 v[40:41], v[0:1], v[32:33]
	v_pk_mul_f32 v[30:31], v[2:3], v[30:31]
	s_nop 0
	v_pk_mul_f32 v[32:33], v[34:35], v[30:31] op_sel_hi:[0,1]
	v_pk_mul_f32 v[30:31], v[34:35], v[40:41] op_sel_hi:[0,1]
	v_add_co_u32_e32 v34, vcc, 0x1000, v38
	s_nop 1
	v_addc_co_u32_e32 v35, vcc, 0, v39, vcc
	global_store_dwordx4 v[34:35], v[30:33], off offset:2048
	s_and_b64 vcc, exec, s[38:39]
	s_cbranch_vccz .LBB0_332
	s_branch .LBB0_333

; template <class T> __device__ __forceinline__ void gst_nt(void* p, T v) { __builtin_nontemporal_store(v, (GAS T*)p); }
; __device__ __forceinline__ float rstd_of(float ss, float inv_n) { return __builtin_amdgcn_rsqf(ss * inv_n + RMS_EPS); }
; __device__ __forceinline__ float bf_lo(unsigned w) { return __uint_as_float(w << 16); }
; __device__ __forceinline__ float bf_hi(unsigned w) { return __uint_as_float(w & 0xffff0000u); }
; __global__ void __launch_bounds__(NWAVES * 64, 2) mk_fwd(Args args) {
;     ...
;                 for (int j = 0; j < 8; ++j) { const f32x4 g = gld<f32x4>(gr + 64 * j);
; #pragma unroll
;                     for (int q = 0; q < 4; ++q) if (q == 0 || mr[q] != m0) {
;                         const float rs = pg8::rstd_of(ss[q], 1.0f / 2048.0f);
;                         gst_nt<f32x4>((f32x4*)(ka->out + (size_t)mr[q] * D) + lane + 64 * j, (f32x4){bf_lo(r[q][j].x), bf_hi(r[q][j].x), bf_lo(r[q][j].y), bf_hi(r[q][j].y)} * g * rs); }
.LBB0_349:
	s_load_dwordx2 s[14:15], s[0:1], 0x98
	v_rsq_f32_e32 v26, v82
	s_lshl_b64 s[40:41], s[44:45], 13
	v_lshlrev_b32_e32 v24, 16, v22
	v_and_b32_e32 v25, 0xffff0000, v22
	s_waitcnt lgkmcnt(0)
	s_add_u32 s14, s14, s40
	s_addc_u32 s15, s15, s41
	v_lshlrev_b32_e32 v22, 16, v23
	v_and_b32_e32 v23, 0xffff0000, v23
	v_lshl_add_u64 v[28:29], s[14:15], 0, v[192:193]
	v_pk_mul_f32 v[30:31], v[0:1], v[24:25]
	v_pk_mul_f32 v[22:23], v[2:3], v[22:23]
	s_nop 0
	v_pk_mul_f32 v[24:25], v[26:27], v[22:23] op_sel_hi:[0,1]
	v_pk_mul_f32 v[22:23], v[26:27], v[30:31] op_sel_hi:[0,1]
	v_add_co_u32_e32 v26, vcc, 0x1000, v28
	s_nop 1
	v_addc_co_u32_e32 v27, vcc, 0, v29, vcc
	global_store_dwordx4 v[26:27], v[22:25], off offset:3072
	s_and_b64 vcc, exec, s[38:39]
	s_cbranch_vccnz .LBB0_302
.LBB0_350:
	s_load_dwordx2 s[14:15], s[0:1], 0x98
	s_lshl_b64 s[2:3], s[2:3], 13
	v_rsq_f32_e32 v22, v80
	v_lshlrev_b32_e32 v24, 16, v20
	v_and_b32_e32 v25, 0xffff0000, v20
	s_waitcnt lgkmcnt(0)
	s_add_u32 s2, s14, s2
	s_addc_u32 s3, s15, s3
	v_lshl_add_u64 v[26:27], s[2:3], 0, v[192:193]
	v_lshlrev_b32_e32 v20, 16, v21
	v_and_b32_e32 v21, 0xffff0000, v21
	v_pk_mul_f32 v[0:1], v[0:1], v[24:25]
	v_pk_mul_f32 v[2:3], v[2:3], v[20:21]
	v_add_co_u32_e32 v20, vcc, 0x1000, v26
	v_pk_mul_f32 v[2:3], v[22:23], v[2:3] op_sel_hi:[0,1]
	v_pk_mul_f32 v[0:1], v[22:23], v[0:1] op_sel_hi:[0,1]
	v_addc_co_u32_e32 v21, vcc, 0, v27, vcc
	global_store_dwordx4 v[20:21], v[0:3], off offset:3072
	s_branch .LBB0_302
